# sample workgroups prefetch the first-block pooling path's Z rows and carried state right after their sub-barrier
# speedup vs baseline: 1.0011x; 1.0011x over previous
.LBB0_228:
	s_movk_i32 s0, 0x1400
	s_movk_i32 s1, 0x14a0
	s_barrier
	v_mbcnt_lo_u32_b32 v240, -1, 0
	v_mbcnt_hi_u32_b32 v240, -1, v240
	v_readlane_b32 s98, v235, 20
	v_lshlrev_b32_e32 v240, 4, v240
	s_nop 3
	s_lshl_b32 s99, s98, 6
	s_add_i32 s99, s99, 0x4000
	s_mul_i32 s99, s99, 0x1040
	v_add_u32_e32 v241, s99, v240
	global_load_dwordx4 v[236:239], v241, s[52:53]
	v_add_u32_e32 v241, 0x1040, v241
	global_load_dwordx4 v[236:239], v241, s[52:53]
	v_add_u32_e32 v241, 0x1040, v241
	global_load_dwordx4 v[236:239], v241, s[52:53]
	v_add_u32_e32 v241, 0x1040, v241
	global_load_dwordx4 v[236:239], v241, s[52:53]
	v_add_u32_e32 v241, 0x1040, v241
	global_load_dwordx4 v[236:239], v241, s[52:53]
	v_add_u32_e32 v241, 0x1040, v241
	global_load_dwordx4 v[236:239], v241, s[52:53]
	v_add_u32_e32 v241, 0x1040, v241
	global_load_dwordx4 v[236:239], v241, s[52:53]
	v_add_u32_e32 v241, 0x1040, v241
	global_load_dwordx4 v[236:239], v241, s[52:53]
	v_add_u32_e32 v241, 0x1040, v241
	global_load_dwordx4 v[236:239], v241, s[52:53]
	v_add_u32_e32 v241, 0x1040, v241
	global_load_dwordx4 v[236:239], v241, s[52:53]
	v_add_u32_e32 v241, 0x1040, v241
	global_load_dwordx4 v[236:239], v241, s[52:53]
	v_add_u32_e32 v241, 0x1040, v241
	global_load_dwordx4 v[236:239], v241, s[52:53]
	v_add_u32_e32 v241, 0x1040, v241
	global_load_dwordx4 v[236:239], v241, s[52:53]
	v_add_u32_e32 v241, 0x1040, v241
	global_load_dwordx4 v[236:239], v241, s[52:53]
	v_add_u32_e32 v241, 0x1040, v241
	global_load_dwordx4 v[236:239], v241, s[52:53]
	v_add_u32_e32 v241, 0x1040, v241
	global_load_dwordx4 v[236:239], v241, s[52:53]
	s_mul_i32 s99, s98, 0x7800
	v_add_u32_e32 v241, s99, v240
	global_load_dwordx4 v[236:239], v241, s[56:57]
	global_load_dwordx4 v[236:239], v241, s[56:57] offset:1024
	global_load_dwordx4 v[236:239], v241, s[56:57] offset:2048
	global_load_dwordx4 v[236:239], v241, s[56:57] offset:3072
	v_add_u32_e32 v241, 0x1000, v241
	global_load_dwordx4 v[236:239], v241, s[56:57]
	global_load_dwordx4 v[236:239], v241, s[56:57] offset:1024
	global_load_dwordx4 v[236:239], v241, s[56:57] offset:2048
	global_load_dwordx4 v[236:239], v241, s[56:57] offset:3072
	v_add_u32_e32 v241, 0x1000, v241
	global_load_dwordx4 v[236:239], v241, s[56:57]
	global_load_dwordx4 v[236:239], v241, s[56:57] offset:1024
	global_load_dwordx4 v[236:239], v241, s[56:57] offset:2048
	global_load_dwordx4 v[236:239], v241, s[56:57] offset:3072
	v_add_u32_e32 v241, 0x1000, v241
	global_load_dwordx4 v[236:239], v241, s[56:57]
	global_load_dwordx4 v[236:239], v241, s[56:57] offset:1024
	global_load_dwordx4 v[236:239], v241, s[56:57] offset:2048
	global_load_dwordx4 v[236:239], v241, s[56:57] offset:3072
	v_add_u32_e32 v241, 0x1000, v241
	global_load_dwordx4 v[236:239], v241, s[56:57]
	global_load_dwordx4 v[236:239], v241, s[56:57] offset:1024
	global_load_dwordx4 v[236:239], v241, s[56:57] offset:2048
	global_load_dwordx4 v[236:239], v241, s[56:57] offset:3072
	v_add_u32_e32 v241, 0x1000, v241
	global_load_dwordx4 v[236:239], v241, s[56:57]
	global_load_dwordx4 v[236:239], v241, s[56:57] offset:1024
	global_load_dwordx4 v[236:239], v241, s[56:57] offset:2048
	global_load_dwordx4 v[236:239], v241, s[56:57] offset:3072
	v_add_u32_e32 v241, 0x1000, v241
	global_load_dwordx4 v[236:239], v241, s[56:57]
	global_load_dwordx4 v[236:239], v241, s[56:57] offset:1024
	global_load_dwordx4 v[236:239], v241, s[56:57] offset:2048
	global_load_dwordx4 v[236:239], v241, s[56:57] offset:3072
	v_add_u32_e32 v241, 0x1000, v241
	global_load_dwordx4 v[236:239], v241, s[56:57]
	global_load_dwordx4 v[236:239], v241, s[56:57] offset:1024

.LBB0_936:
	s_movk_i32 s0, 0x1400
	s_barrier
	v_mbcnt_lo_u32_b32 v240, -1, 0
	v_mbcnt_hi_u32_b32 v240, -1, v240
	v_readlane_b32 s98, v235, 20
	v_lshlrev_b32_e32 v240, 4, v240
	s_nop 3
	s_lshl_b32 s99, s98, 6
	s_add_i32 s99, s99, 0x4000
	s_mul_i32 s99, s99, 0x1040
	v_add_u32_e32 v241, s99, v240
	global_load_dwordx4 v[236:239], v241, s[52:53]
	v_add_u32_e32 v241, 0x1040, v241
	global_load_dwordx4 v[236:239], v241, s[52:53]
	v_add_u32_e32 v241, 0x1040, v241
	global_load_dwordx4 v[236:239], v241, s[52:53]
	v_add_u32_e32 v241, 0x1040, v241
	global_load_dwordx4 v[236:239], v241, s[52:53]
	v_add_u32_e32 v241, 0x1040, v241
	global_load_dwordx4 v[236:239], v241, s[52:53]
	v_add_u32_e32 v241, 0x1040, v241
	global_load_dwordx4 v[236:239], v241, s[52:53]
	v_add_u32_e32 v241, 0x1040, v241
	global_load_dwordx4 v[236:239], v241, s[52:53]
	v_add_u32_e32 v241, 0x1040, v241
	global_load_dwordx4 v[236:239], v241, s[52:53]
	v_add_u32_e32 v241, 0x1040, v241
	global_load_dwordx4 v[236:239], v241, s[52:53]
	v_add_u32_e32 v241, 0x1040, v241
	global_load_dwordx4 v[236:239], v241, s[52:53]
	v_add_u32_e32 v241, 0x1040, v241
	global_load_dwordx4 v[236:239], v241, s[52:53]
	v_add_u32_e32 v241, 0x1040, v241
	global_load_dwordx4 v[236:239], v241, s[52:53]
	v_add_u32_e32 v241, 0x1040, v241
	global_load_dwordx4 v[236:239], v241, s[52:53]
	v_add_u32_e32 v241, 0x1040, v241
	global_load_dwordx4 v[236:239], v241, s[52:53]
	v_add_u32_e32 v241, 0x1040, v241
	global_load_dwordx4 v[236:239], v241, s[52:53]
	v_add_u32_e32 v241, 0x1040, v241
	global_load_dwordx4 v[236:239], v241, s[52:53]
	s_mul_i32 s99, s98, 0x7800
	s_add_i32 s99, s99, 0x3c000
	v_add_u32_e32 v241, s99, v240
	global_load_dwordx4 v[236:239], v241, s[56:57]
	global_load_dwordx4 v[236:239], v241, s[56:57] offset:1024
	global_load_dwordx4 v[236:239], v241, s[56:57] offset:2048
	global_load_dwordx4 v[236:239], v241, s[56:57] offset:3072
	v_add_u32_e32 v241, 0x1000, v241
	global_load_dwordx4 v[236:239], v241, s[56:57]
	global_load_dwordx4 v[236:239], v241, s[56:57] offset:1024
	global_load_dwordx4 v[236:239], v241, s[56:57] offset:2048
	global_load_dwordx4 v[236:239], v241, s[56:57] offset:3072
	v_add_u32_e32 v241, 0x1000, v241
	global_load_dwordx4 v[236:239], v241, s[56:57]
	global_load_dwordx4 v[236:239], v241, s[56:57] offset:1024
	global_load_dwordx4 v[236:239], v241, s[56:57] offset:2048
	global_load_dwordx4 v[236:239], v241, s[56:57] offset:3072
	v_add_u32_e32 v241, 0x1000, v241
	global_load_dwordx4 v[236:239], v241, s[56:57]
	global_load_dwordx4 v[236:239], v241, s[56:57] offset:1024
	global_load_dwordx4 v[236:239], v241, s[56:57] offset:2048
	global_load_dwordx4 v[236:239], v241, s[56:57] offset:3072
	v_add_u32_e32 v241, 0x1000, v241
	global_load_dwordx4 v[236:239], v241, s[56:57]
	global_load_dwordx4 v[236:239], v241, s[56:57] offset:1024
	global_load_dwordx4 v[236:239], v241, s[56:57] offset:2048
	global_load_dwordx4 v[236:239], v241, s[56:57] offset:3072
	v_add_u32_e32 v241, 0x1000, v241
	global_load_dwordx4 v[236:239], v241, s[56:57]
	global_load_dwordx4 v[236:239], v241, s[56:57] offset:1024
	global_load_dwordx4 v[236:239], v241, s[56:57] offset:2048
	global_load_dwordx4 v[236:239], v241, s[56:57] offset:3072
	v_add_u32_e32 v241, 0x1000, v241
	global_load_dwordx4 v[236:239], v241, s[56:57]
	global_load_dwordx4 v[236:239], v241, s[56:57] offset:1024
	global_load_dwordx4 v[236:239], v241, s[56:57] offset:2048
	global_load_dwordx4 v[236:239], v241, s[56:57] offset:3072
	v_add_u32_e32 v241, 0x1000, v241
	global_load_dwordx4 v[236:239], v241, s[56:57]
	global_load_dwordx4 v[236:239], v241, s[56:57] offset:1024

.LBB0_1645:
	s_movk_i32 s0, 0x1400
	s_barrier
	v_mbcnt_lo_u32_b32 v240, -1, 0
	v_mbcnt_hi_u32_b32 v240, -1, v240
	v_readlane_b32 s98, v235, 20
	v_lshlrev_b32_e32 v240, 4, v240
	s_nop 3
	s_lshl_b32 s99, s98, 6
	s_add_i32 s99, s99, 0x4000
	s_mul_i32 s99, s99, 0x1040
	v_add_u32_e32 v241, s99, v240
	global_load_dwordx4 v[236:239], v241, s[52:53]
	v_add_u32_e32 v241, 0x1040, v241
	global_load_dwordx4 v[236:239], v241, s[52:53]
	v_add_u32_e32 v241, 0x1040, v241
	global_load_dwordx4 v[236:239], v241, s[52:53]
	v_add_u32_e32 v241, 0x1040, v241
	global_load_dwordx4 v[236:239], v241, s[52:53]
	v_add_u32_e32 v241, 0x1040, v241
	global_load_dwordx4 v[236:239], v241, s[52:53]
	v_add_u32_e32 v241, 0x1040, v241
	global_load_dwordx4 v[236:239], v241, s[52:53]
	v_add_u32_e32 v241, 0x1040, v241
	global_load_dwordx4 v[236:239], v241, s[52:53]
	v_add_u32_e32 v241, 0x1040, v241
	global_load_dwordx4 v[236:239], v241, s[52:53]
	v_add_u32_e32 v241, 0x1040, v241
	global_load_dwordx4 v[236:239], v241, s[52:53]
	v_add_u32_e32 v241, 0x1040, v241
	global_load_dwordx4 v[236:239], v241, s[52:53]
	v_add_u32_e32 v241, 0x1040, v241
	global_load_dwordx4 v[236:239], v241, s[52:53]
	v_add_u32_e32 v241, 0x1040, v241
	global_load_dwordx4 v[236:239], v241, s[52:53]
	v_add_u32_e32 v241, 0x1040, v241
	global_load_dwordx4 v[236:239], v241, s[52:53]
	v_add_u32_e32 v241, 0x1040, v241
	global_load_dwordx4 v[236:239], v241, s[52:53]
	v_add_u32_e32 v241, 0x1040, v241
	global_load_dwordx4 v[236:239], v241, s[52:53]
	v_add_u32_e32 v241, 0x1040, v241
	global_load_dwordx4 v[236:239], v241, s[52:53]
	s_mul_i32 s99, s98, 0x7800
	s_add_i32 s99, s99, 0x78000
	v_add_u32_e32 v241, s99, v240
	global_load_dwordx4 v[236:239], v241, s[56:57]
	global_load_dwordx4 v[236:239], v241, s[56:57] offset:1024
	global_load_dwordx4 v[236:239], v241, s[56:57] offset:2048
	global_load_dwordx4 v[236:239], v241, s[56:57] offset:3072
	v_add_u32_e32 v241, 0x1000, v241
	global_load_dwordx4 v[236:239], v241, s[56:57]
	global_load_dwordx4 v[236:239], v241, s[56:57] offset:1024
	global_load_dwordx4 v[236:239], v241, s[56:57] offset:2048
	global_load_dwordx4 v[236:239], v241, s[56:57] offset:3072
	v_add_u32_e32 v241, 0x1000, v241
	global_load_dwordx4 v[236:239], v241, s[56:57]
	global_load_dwordx4 v[236:239], v241, s[56:57] offset:1024
	global_load_dwordx4 v[236:239], v241, s[56:57] offset:2048
	global_load_dwordx4 v[236:239], v241, s[56:57] offset:3072
	v_add_u32_e32 v241, 0x1000, v241
	global_load_dwordx4 v[236:239], v241, s[56:57]
	global_load_dwordx4 v[236:239], v241, s[56:57] offset:1024
	global_load_dwordx4 v[236:239], v241, s[56:57] offset:2048
	global_load_dwordx4 v[236:239], v241, s[56:57] offset:3072
	v_add_u32_e32 v241, 0x1000, v241
	global_load_dwordx4 v[236:239], v241, s[56:57]
	global_load_dwordx4 v[236:239], v241, s[56:57] offset:1024
	global_load_dwordx4 v[236:239], v241, s[56:57] offset:2048
	global_load_dwordx4 v[236:239], v241, s[56:57] offset:3072
	v_add_u32_e32 v241, 0x1000, v241
	global_load_dwordx4 v[236:239], v241, s[56:57]
	global_load_dwordx4 v[236:239], v241, s[56:57] offset:1024
	global_load_dwordx4 v[236:239], v241, s[56:57] offset:2048
	global_load_dwordx4 v[236:239], v241, s[56:57] offset:3072
	v_add_u32_e32 v241, 0x1000, v241
	global_load_dwordx4 v[236:239], v241, s[56:57]
	global_load_dwordx4 v[236:239], v241, s[56:57] offset:1024
	global_load_dwordx4 v[236:239], v241, s[56:57] offset:2048
	global_load_dwordx4 v[236:239], v241, s[56:57] offset:3072
	v_add_u32_e32 v241, 0x1000, v241
	global_load_dwordx4 v[236:239], v241, s[56:57]
	global_load_dwordx4 v[236:239], v241, s[56:57] offset:1024

.LBB0_2354:
	s_movk_i32 s0, 0x1400
	s_barrier
	v_mbcnt_lo_u32_b32 v240, -1, 0
	v_mbcnt_hi_u32_b32 v240, -1, v240
	v_readlane_b32 s98, v235, 20
	v_lshlrev_b32_e32 v240, 4, v240
	s_nop 3
	s_lshl_b32 s99, s98, 6
	s_add_i32 s99, s99, 0x4000
	s_mul_i32 s99, s99, 0x1040
	v_add_u32_e32 v241, s99, v240
	global_load_dwordx4 v[236:239], v241, s[52:53]
	v_add_u32_e32 v241, 0x1040, v241
	global_load_dwordx4 v[236:239], v241, s[52:53]
	v_add_u32_e32 v241, 0x1040, v241
	global_load_dwordx4 v[236:239], v241, s[52:53]
	v_add_u32_e32 v241, 0x1040, v241
	global_load_dwordx4 v[236:239], v241, s[52:53]
	v_add_u32_e32 v241, 0x1040, v241
	global_load_dwordx4 v[236:239], v241, s[52:53]
	v_add_u32_e32 v241, 0x1040, v241
	global_load_dwordx4 v[236:239], v241, s[52:53]
	v_add_u32_e32 v241, 0x1040, v241
	global_load_dwordx4 v[236:239], v241, s[52:53]
	v_add_u32_e32 v241, 0x1040, v241
	global_load_dwordx4 v[236:239], v241, s[52:53]
	v_add_u32_e32 v241, 0x1040, v241
	global_load_dwordx4 v[236:239], v241, s[52:53]
	v_add_u32_e32 v241, 0x1040, v241
	global_load_dwordx4 v[236:239], v241, s[52:53]
	v_add_u32_e32 v241, 0x1040, v241
	global_load_dwordx4 v[236:239], v241, s[52:53]
	v_add_u32_e32 v241, 0x1040, v241
	global_load_dwordx4 v[236:239], v241, s[52:53]
	v_add_u32_e32 v241, 0x1040, v241
	global_load_dwordx4 v[236:239], v241, s[52:53]
	v_add_u32_e32 v241, 0x1040, v241
	global_load_dwordx4 v[236:239], v241, s[52:53]
	v_add_u32_e32 v241, 0x1040, v241
	global_load_dwordx4 v[236:239], v241, s[52:53]
	v_add_u32_e32 v241, 0x1040, v241
	global_load_dwordx4 v[236:239], v241, s[52:53]
	s_mul_i32 s99, s98, 0x7800
	s_add_i32 s99, s99, 0xb4000
	v_add_u32_e32 v241, s99, v240
	global_load_dwordx4 v[236:239], v241, s[56:57]
	global_load_dwordx4 v[236:239], v241, s[56:57] offset:1024
	global_load_dwordx4 v[236:239], v241, s[56:57] offset:2048
	global_load_dwordx4 v[236:239], v241, s[56:57] offset:3072
	v_add_u32_e32 v241, 0x1000, v241
	global_load_dwordx4 v[236:239], v241, s[56:57]
	global_load_dwordx4 v[236:239], v241, s[56:57] offset:1024
	global_load_dwordx4 v[236:239], v241, s[56:57] offset:2048
	global_load_dwordx4 v[236:239], v241, s[56:57] offset:3072
	v_add_u32_e32 v241, 0x1000, v241
	global_load_dwordx4 v[236:239], v241, s[56:57]
	global_load_dwordx4 v[236:239], v241, s[56:57] offset:1024
	global_load_dwordx4 v[236:239], v241, s[56:57] offset:2048
	global_load_dwordx4 v[236:239], v241, s[56:57] offset:3072
	v_add_u32_e32 v241, 0x1000, v241
	global_load_dwordx4 v[236:239], v241, s[56:57]
	global_load_dwordx4 v[236:239], v241, s[56:57] offset:1024
	global_load_dwordx4 v[236:239], v241, s[56:57] offset:2048
	global_load_dwordx4 v[236:239], v241, s[56:57] offset:3072
	v_add_u32_e32 v241, 0x1000, v241
	global_load_dwordx4 v[236:239], v241, s[56:57]
	global_load_dwordx4 v[236:239], v241, s[56:57] offset:1024
	global_load_dwordx4 v[236:239], v241, s[56:57] offset:2048
	global_load_dwordx4 v[236:239], v241, s[56:57] offset:3072
	v_add_u32_e32 v241, 0x1000, v241
	global_load_dwordx4 v[236:239], v241, s[56:57]
	global_load_dwordx4 v[236:239], v241, s[56:57] offset:1024
	global_load_dwordx4 v[236:239], v241, s[56:57] offset:2048
	global_load_dwordx4 v[236:239], v241, s[56:57] offset:3072
	v_add_u32_e32 v241, 0x1000, v241
	global_load_dwordx4 v[236:239], v241, s[56:57]
	global_load_dwordx4 v[236:239], v241, s[56:57] offset:1024
	global_load_dwordx4 v[236:239], v241, s[56:57] offset:2048
	global_load_dwordx4 v[236:239], v241, s[56:57] offset:3072
	v_add_u32_e32 v241, 0x1000, v241
	global_load_dwordx4 v[236:239], v241, s[56:57]
	global_load_dwordx4 v[236:239], v241, s[56:57] offset:1024
